# down-proj GEMM epilogue: bf16 residual loads software-pipelined 8 deep with counted vmcnt instead of load+vmcnt(0) per 8 outputs
# speedup vs baseline: 1.0064x; 1.0064x over previous
;     __device__ __forceinline__ void operator()(const f32x4 (&acc)[2][2][4][2], const Unit& u, int wr, int wc, int fr, int fq) const {
;         const int row0 = u.pm * BM + wr * 64 + fr, col0 = u.pn * BM + wc * 32 + 8 * fq;
; #pragma unroll
;         for (int ai = 0; ai < 2; ++ai)
; #pragma unroll
;             for (int m = 0; m < 4; ++m) { const size_t off = (size_t)(row0 + ai * HALF + m * 16) * ldc + col0;
; #pragma unroll
;                 for (int bj = 0; bj < 2; ++bj) { const u32x4 w = *(const u32x4*)(hb + off + bj * HALF);
;                     const f32x4 h0 = {__builtin_bit_cast(float, w.x << 16), __builtin_bit_cast(float, w.x & 0xffff0000u), __builtin_bit_cast(float, w.y << 16), __builtin_bit_cast(float, w.y & 0xffff0000u)};
;                     const f32x4 h1 = {__builtin_bit_cast(float, w.z << 16), __builtin_bit_cast(float, w.z & 0xffff0000u), __builtin_bit_cast(float, w.w << 16), __builtin_bit_cast(float, w.w & 0xffff0000u)};
;                     __builtin_nontemporal_store(h0 + acc[ai][bj][m][0], (f32x4*)(out + off + bj * HALF)); __builtin_nontemporal_store(h1 + acc[ai][bj][m][1], (f32x4*)(out + off + bj * HALF + 4)); } }
;     }
.LBB0_794:
	v_lshl_add_u32 v148, s49, 8, v150
	v_lshl_or_b32 v146, s50, 8, v152
	v_ashrrev_i32_e32 v147, 31, v146
	s_and_b64 vcc, exec, s[0:1]
	s_mov_b64 s[0:1], -1
	v_mov_b32_e32 v144, v148
	v_ashrrev_i32_e32 v145, 31, v144
	v_lshlrev_b64 v[144:145], 11, v[144:145]
	v_lshl_add_u64 v[144:145], v[144:145], 0, v[146:147]
	v_lshl_add_u64 v[160:161], v[144:145], 1, s[6:7]
	global_load_dwordx4 v[224:227], v[160:161], off
	global_load_dwordx4 v[228:231], v[160:161], off offset:256
	v_or_b32_e32 v144, 0x10, v148
	v_ashrrev_i32_e32 v145, 31, v144
	v_lshlrev_b64 v[144:145], 11, v[144:145]
	v_lshl_add_u64 v[144:145], v[144:145], 0, v[146:147]
	v_lshl_add_u64 v[160:161], v[144:145], 1, s[6:7]
	global_load_dwordx4 v[232:235], v[160:161], off
	global_load_dwordx4 v[236:239], v[160:161], off offset:256
	v_or_b32_e32 v144, 0x20, v148
	v_ashrrev_i32_e32 v145, 31, v144
	v_lshlrev_b64 v[144:145], 11, v[144:145]
	v_lshl_add_u64 v[144:145], v[144:145], 0, v[146:147]
	v_lshl_add_u64 v[160:161], v[144:145], 1, s[6:7]
	global_load_dwordx4 v[240:243], v[160:161], off
	global_load_dwordx4 v[244:247], v[160:161], off offset:256
	v_or_b32_e32 v144, 0x30, v148
	v_ashrrev_i32_e32 v145, 31, v144
	v_lshlrev_b64 v[144:145], 11, v[144:145]
	v_lshl_add_u64 v[144:145], v[144:145], 0, v[146:147]
	v_lshl_add_u64 v[160:161], v[144:145], 1, s[6:7]
	global_load_dwordx4 v[248:251], v[160:161], off
	global_load_dwordx4 v[252:255], v[160:161], off offset:256
	v_mov_b32_e32 v144, v148
	v_ashrrev_i32_e32 v145, 31, v144
	v_lshlrev_b64 v[144:145], 11, v[144:145]
	v_lshl_add_u64 v[144:145], v[144:145], 0, v[146:147]
	v_lshl_add_u64 v[162:163], v[144:145], 2, s[58:59]
	s_waitcnt vmcnt(7)
	v_lshlrev_b32_e32 v164, 16, v224
	v_and_b32_e32 v165, 0xffff0000, v224
	v_lshlrev_b32_e32 v156, 16, v225
	v_and_b32_e32 v157, 0xffff0000, v225
	v_lshlrev_b32_e32 v166, 16, v226
	v_and_b32_e32 v167, 0xffff0000, v226
	v_lshlrev_b32_e32 v158, 16, v227
	v_and_b32_e32 v159, 0xffff0000, v227
	v_pk_add_f32 v[126:127], v[126:127], v[156:157]
	v_pk_add_f32 v[124:125], v[124:125], v[164:165]
	v_pk_add_f32 v[122:123], v[122:123], v[158:159]
	v_pk_add_f32 v[120:121], v[120:121], v[166:167]
	global_store_dwordx4 v[162:163], v[124:127], off nt
	global_store_dwordx4 v[162:163], v[120:123], off offset:16 nt
	s_waitcnt vmcnt(8)
	v_lshlrev_b32_e32 v164, 16, v228
	v_and_b32_e32 v165, 0xffff0000, v228
	v_lshlrev_b32_e32 v156, 16, v229
	v_and_b32_e32 v157, 0xffff0000, v229
	v_lshlrev_b32_e32 v166, 16, v230
	v_and_b32_e32 v167, 0xffff0000, v230
	v_lshlrev_b32_e32 v158, 16, v231
	v_and_b32_e32 v159, 0xffff0000, v231
	v_pk_add_f32 v[118:119], v[118:119], v[156:157]
	v_pk_add_f32 v[116:117], v[116:117], v[164:165]
	v_pk_add_f32 v[114:115], v[114:115], v[158:159]
	v_pk_add_f32 v[112:113], v[112:113], v[166:167]
	global_store_dwordx4 v[162:163], v[116:119], off offset:512 nt
	global_store_dwordx4 v[162:163], v[112:115], off offset:528 nt
	v_or_b32_e32 v144, 0x80, v148
	v_ashrrev_i32_e32 v145, 31, v144
	v_lshlrev_b64 v[144:145], 11, v[144:145]
	v_lshl_add_u64 v[144:145], v[144:145], 0, v[146:147]
	v_lshl_add_u64 v[160:161], v[144:145], 1, s[6:7]
	global_load_dwordx4 v[224:227], v[160:161], off
	global_load_dwordx4 v[228:231], v[160:161], off offset:256
	v_or_b32_e32 v144, 0x10, v148
	v_ashrrev_i32_e32 v145, 31, v144
	v_lshlrev_b64 v[144:145], 11, v[144:145]
	v_lshl_add_u64 v[144:145], v[144:145], 0, v[146:147]
	v_lshl_add_u64 v[162:163], v[144:145], 2, s[58:59]
	s_waitcnt vmcnt(11)
	v_lshlrev_b32_e32 v164, 16, v232
	v_and_b32_e32 v165, 0xffff0000, v232
	v_lshlrev_b32_e32 v156, 16, v233
	v_and_b32_e32 v157, 0xffff0000, v233
	v_lshlrev_b32_e32 v166, 16, v234
	v_and_b32_e32 v167, 0xffff0000, v234
	v_lshlrev_b32_e32 v158, 16, v235
	v_and_b32_e32 v159, 0xffff0000, v235
	v_pk_add_f32 v[110:111], v[110:111], v[156:157]
	v_pk_add_f32 v[108:109], v[108:109], v[164:165]
	v_pk_add_f32 v[106:107], v[106:107], v[158:159]
	v_pk_add_f32 v[104:105], v[104:105], v[166:167]
	global_store_dwordx4 v[162:163], v[108:111], off nt
	global_store_dwordx4 v[162:163], v[104:107], off offset:16 nt
	s_waitcnt vmcnt(12)
	v_lshlrev_b32_e32 v164, 16, v236
	v_and_b32_e32 v165, 0xffff0000, v236
	v_lshlrev_b32_e32 v156, 16, v237
	v_and_b32_e32 v157, 0xffff0000, v237
	v_lshlrev_b32_e32 v166, 16, v238
	v_and_b32_e32 v167, 0xffff0000, v238
	v_lshlrev_b32_e32 v158, 16, v239
	v_and_b32_e32 v159, 0xffff0000, v239
	v_pk_add_f32 v[102:103], v[102:103], v[156:157]
	v_pk_add_f32 v[100:101], v[100:101], v[164:165]
	v_pk_add_f32 v[98:99], v[98:99], v[158:159]
	v_pk_add_f32 v[96:97], v[96:97], v[166:167]
	global_store_dwordx4 v[162:163], v[100:103], off offset:512 nt
	global_store_dwordx4 v[162:163], v[96:99], off offset:528 nt
	v_or_b32_e32 v144, 0x90, v148
	v_ashrrev_i32_e32 v145, 31, v144
	v_lshlrev_b64 v[144:145], 11, v[144:145]
	v_lshl_add_u64 v[144:145], v[144:145], 0, v[146:147]
	v_lshl_add_u64 v[160:161], v[144:145], 1, s[6:7]
	global_load_dwordx4 v[232:235], v[160:161], off
	global_load_dwordx4 v[236:239], v[160:161], off offset:256
	v_or_b32_e32 v144, 0x20, v148
	v_ashrrev_i32_e32 v145, 31, v144
	v_lshlrev_b64 v[144:145], 11, v[144:145]
	v_lshl_add_u64 v[144:145], v[144:145], 0, v[146:147]
	v_lshl_add_u64 v[162:163], v[144:145], 2, s[58:59]
	s_waitcnt vmcnt(15)
	v_lshlrev_b32_e32 v164, 16, v240
	v_and_b32_e32 v165, 0xffff0000, v240
	v_lshlrev_b32_e32 v156, 16, v241
	v_and_b32_e32 v157, 0xffff0000, v241
	v_lshlrev_b32_e32 v166, 16, v242
	v_and_b32_e32 v167, 0xffff0000, v242
	v_lshlrev_b32_e32 v158, 16, v243
	v_and_b32_e32 v159, 0xffff0000, v243
	v_pk_add_f32 v[94:95], v[94:95], v[156:157]
	v_pk_add_f32 v[92:93], v[92:93], v[164:165]
	v_pk_add_f32 v[90:91], v[90:91], v[158:159]
	v_pk_add_f32 v[88:89], v[88:89], v[166:167]
	global_store_dwordx4 v[162:163], v[92:95], off nt
	global_store_dwordx4 v[162:163], v[88:91], off offset:16 nt
	s_waitcnt vmcnt(16)
;     __device__ __forceinline__ void operator()(const f32x4 (&acc)[2][2][4][2], const Unit& u, int wr, int wc, int fr, int fq) const {
;     ...
;         for (int ai = 0; ai < 2; ++ai)
; #pragma unroll
;             for (int m = 0; m < 4; ++m) { const size_t off = (size_t)(row0 + ai * HALF + m * 16) * ldc + col0;
; #pragma unroll
;                 for (int bj = 0; bj < 2; ++bj) { const u32x4 w = *(const u32x4*)(hb + off + bj * HALF);
;                     const f32x4 h0 = {__builtin_bit_cast(float, w.x << 16), __builtin_bit_cast(float, w.x & 0xffff0000u), __builtin_bit_cast(float, w.y << 16), __builtin_bit_cast(float, w.y & 0xffff0000u)};
;                     const f32x4 h1 = {__builtin_bit_cast(float, w.z << 16), __builtin_bit_cast(float, w.z & 0xffff0000u), __builtin_bit_cast(float, w.w << 16), __builtin_bit_cast(float, w.w & 0xffff0000u)};
;                     __builtin_nontemporal_store(h0 + acc[ai][bj][m][0], (f32x4*)(out + off + bj * HALF)); __builtin_nontemporal_store(h1 + acc[ai][bj][m][1], (f32x4*)(out + off + bj * HALF + 4)); } }
	v_lshlrev_b32_e32 v164, 16, v244
	v_and_b32_e32 v165, 0xffff0000, v244
	v_lshlrev_b32_e32 v156, 16, v245
	v_and_b32_e32 v157, 0xffff0000, v245
	v_lshlrev_b32_e32 v166, 16, v246
	v_and_b32_e32 v167, 0xffff0000, v246
	v_lshlrev_b32_e32 v158, 16, v247
	v_and_b32_e32 v159, 0xffff0000, v247
	v_pk_add_f32 v[86:87], v[86:87], v[156:157]
	v_pk_add_f32 v[84:85], v[84:85], v[164:165]
	v_pk_add_f32 v[82:83], v[82:83], v[158:159]
	v_pk_add_f32 v[80:81], v[80:81], v[166:167]
	global_store_dwordx4 v[162:163], v[84:87], off offset:512 nt
	global_store_dwordx4 v[162:163], v[80:83], off offset:528 nt
	v_or_b32_e32 v144, 0xa0, v148
	v_ashrrev_i32_e32 v145, 31, v144
	v_lshlrev_b64 v[144:145], 11, v[144:145]
	v_lshl_add_u64 v[144:145], v[144:145], 0, v[146:147]
	v_lshl_add_u64 v[160:161], v[144:145], 1, s[6:7]
	global_load_dwordx4 v[240:243], v[160:161], off
	global_load_dwordx4 v[244:247], v[160:161], off offset:256
	v_or_b32_e32 v144, 0x30, v148
	v_ashrrev_i32_e32 v145, 31, v144
	v_lshlrev_b64 v[144:145], 11, v[144:145]
	v_lshl_add_u64 v[144:145], v[144:145], 0, v[146:147]
	v_lshl_add_u64 v[162:163], v[144:145], 2, s[58:59]
	s_waitcnt vmcnt(19)
	v_lshlrev_b32_e32 v164, 16, v248
	v_and_b32_e32 v165, 0xffff0000, v248
	v_lshlrev_b32_e32 v156, 16, v249
	v_and_b32_e32 v157, 0xffff0000, v249
	v_lshlrev_b32_e32 v166, 16, v250
	v_and_b32_e32 v167, 0xffff0000, v250
	v_lshlrev_b32_e32 v158, 16, v251
	v_and_b32_e32 v159, 0xffff0000, v251
	v_pk_add_f32 v[78:79], v[78:79], v[156:157]
	v_pk_add_f32 v[76:77], v[76:77], v[164:165]
	v_pk_add_f32 v[74:75], v[74:75], v[158:159]
	v_pk_add_f32 v[72:73], v[72:73], v[166:167]
	global_store_dwordx4 v[162:163], v[76:79], off nt
	global_store_dwordx4 v[162:163], v[72:75], off offset:16 nt
	s_waitcnt vmcnt(20)
	v_lshlrev_b32_e32 v164, 16, v252
	v_and_b32_e32 v165, 0xffff0000, v252
	v_lshlrev_b32_e32 v156, 16, v253
	v_and_b32_e32 v157, 0xffff0000, v253
	v_lshlrev_b32_e32 v166, 16, v254
	v_and_b32_e32 v167, 0xffff0000, v254
	v_lshlrev_b32_e32 v158, 16, v255
	v_and_b32_e32 v159, 0xffff0000, v255
	v_pk_add_f32 v[70:71], v[70:71], v[156:157]
	v_pk_add_f32 v[68:69], v[68:69], v[164:165]
	v_pk_add_f32 v[66:67], v[66:67], v[158:159]
	v_pk_add_f32 v[64:65], v[64:65], v[166:167]
	global_store_dwordx4 v[162:163], v[68:71], off offset:512 nt
	global_store_dwordx4 v[162:163], v[64:67], off offset:528 nt
	v_or_b32_e32 v144, 0xb0, v148
	v_ashrrev_i32_e32 v145, 31, v144
	v_lshlrev_b64 v[144:145], 11, v[144:145]
	v_lshl_add_u64 v[144:145], v[144:145], 0, v[146:147]
	v_lshl_add_u64 v[160:161], v[144:145], 1, s[6:7]
	global_load_dwordx4 v[248:251], v[160:161], off
	global_load_dwordx4 v[252:255], v[160:161], off offset:256
	v_or_b32_e32 v144, 0x80, v148
	v_ashrrev_i32_e32 v145, 31, v144
	v_lshlrev_b64 v[144:145], 11, v[144:145]
	v_lshl_add_u64 v[144:145], v[144:145], 0, v[146:147]
	v_lshl_add_u64 v[162:163], v[144:145], 2, s[58:59]
	s_waitcnt vmcnt(19)
	v_lshlrev_b32_e32 v164, 16, v224
	v_and_b32_e32 v165, 0xffff0000, v224
	v_lshlrev_b32_e32 v156, 16, v225
	v_and_b32_e32 v157, 0xffff0000, v225
	v_lshlrev_b32_e32 v166, 16, v226
	v_and_b32_e32 v167, 0xffff0000, v226
	v_lshlrev_b32_e32 v158, 16, v227
	v_and_b32_e32 v159, 0xffff0000, v227
	v_pk_add_f32 v[62:63], v[62:63], v[156:157]
	v_pk_add_f32 v[60:61], v[60:61], v[164:165]
	v_pk_add_f32 v[58:59], v[58:59], v[158:159]
	v_pk_add_f32 v[56:57], v[56:57], v[166:167]
	global_store_dwordx4 v[162:163], v[60:63], off nt
	global_store_dwordx4 v[162:163], v[56:59], off offset:16 nt
	s_waitcnt vmcnt(20)
	v_lshlrev_b32_e32 v164, 16, v228
	v_and_b32_e32 v165, 0xffff0000, v228
	v_lshlrev_b32_e32 v156, 16, v229
	v_and_b32_e32 v157, 0xffff0000, v229
	v_lshlrev_b32_e32 v166, 16, v230
	v_and_b32_e32 v167, 0xffff0000, v230
	v_lshlrev_b32_e32 v158, 16, v231
	v_and_b32_e32 v159, 0xffff0000, v231
	v_pk_add_f32 v[54:55], v[54:55], v[156:157]
	v_pk_add_f32 v[52:53], v[52:53], v[164:165]
	v_pk_add_f32 v[50:51], v[50:51], v[158:159]
	v_pk_add_f32 v[48:49], v[48:49], v[166:167]
	global_store_dwordx4 v[162:163], v[52:55], off offset:512 nt
	global_store_dwordx4 v[162:163], v[48:51], off offset:528 nt
	v_or_b32_e32 v144, 0x90, v148
	v_ashrrev_i32_e32 v145, 31, v144
	v_lshlrev_b64 v[144:145], 11, v[144:145]
	v_lshl_add_u64 v[144:145], v[144:145], 0, v[146:147]
	v_lshl_add_u64 v[162:163], v[144:145], 2, s[58:59]
	s_waitcnt vmcnt(17)
;     __device__ __forceinline__ void operator()(const f32x4 (&acc)[2][2][4][2], const Unit& u, int wr, int wc, int fr, int fq) const {
;     ...
;         for (int ai = 0; ai < 2; ++ai)
; #pragma unroll
;             for (int m = 0; m < 4; ++m) { const size_t off = (size_t)(row0 + ai * HALF + m * 16) * ldc + col0;
; #pragma unroll
;                 for (int bj = 0; bj < 2; ++bj) { const u32x4 w = *(const u32x4*)(hb + off + bj * HALF);
;                     const f32x4 h0 = {__builtin_bit_cast(float, w.x << 16), __builtin_bit_cast(float, w.x & 0xffff0000u), __builtin_bit_cast(float, w.y << 16), __builtin_bit_cast(float, w.y & 0xffff0000u)};
;                     const f32x4 h1 = {__builtin_bit_cast(float, w.z << 16), __builtin_bit_cast(float, w.z & 0xffff0000u), __builtin_bit_cast(float, w.w << 16), __builtin_bit_cast(float, w.w & 0xffff0000u)};
;                     __builtin_nontemporal_store(h0 + acc[ai][bj][m][0], (f32x4*)(out + off + bj * HALF)); __builtin_nontemporal_store(h1 + acc[ai][bj][m][1], (f32x4*)(out + off + bj * HALF + 4)); } }
;     }
	v_lshlrev_b32_e32 v164, 16, v232
	v_and_b32_e32 v165, 0xffff0000, v232
	v_lshlrev_b32_e32 v156, 16, v233
	v_and_b32_e32 v157, 0xffff0000, v233
	v_lshlrev_b32_e32 v166, 16, v234
	v_and_b32_e32 v167, 0xffff0000, v234
	v_lshlrev_b32_e32 v158, 16, v235
	v_and_b32_e32 v159, 0xffff0000, v235
	v_pk_add_f32 v[46:47], v[46:47], v[156:157]
	v_pk_add_f32 v[44:45], v[44:45], v[164:165]
	v_pk_add_f32 v[42:43], v[42:43], v[158:159]
	v_pk_add_f32 v[40:41], v[40:41], v[166:167]
	global_store_dwordx4 v[162:163], v[44:47], off nt
	global_store_dwordx4 v[162:163], v[40:43], off offset:16 nt
	s_waitcnt vmcnt(18)
	v_lshlrev_b32_e32 v164, 16, v236
	v_and_b32_e32 v165, 0xffff0000, v236
	v_lshlrev_b32_e32 v156, 16, v237
	v_and_b32_e32 v157, 0xffff0000, v237
	v_lshlrev_b32_e32 v166, 16, v238
	v_and_b32_e32 v167, 0xffff0000, v238
	v_lshlrev_b32_e32 v158, 16, v239
	v_and_b32_e32 v159, 0xffff0000, v239
	v_pk_add_f32 v[38:39], v[38:39], v[156:157]
	v_pk_add_f32 v[36:37], v[36:37], v[164:165]
	v_pk_add_f32 v[34:35], v[34:35], v[158:159]
	v_pk_add_f32 v[32:33], v[32:33], v[166:167]
	global_store_dwordx4 v[162:163], v[36:39], off offset:512 nt
	global_store_dwordx4 v[162:163], v[32:35], off offset:528 nt
	v_or_b32_e32 v144, 0xa0, v148
	v_ashrrev_i32_e32 v145, 31, v144
	v_lshlrev_b64 v[144:145], 11, v[144:145]
	v_lshl_add_u64 v[144:145], v[144:145], 0, v[146:147]
	v_lshl_add_u64 v[162:163], v[144:145], 2, s[58:59]
	s_waitcnt vmcnt(15)
	v_lshlrev_b32_e32 v164, 16, v240
	v_and_b32_e32 v165, 0xffff0000, v240
	v_lshlrev_b32_e32 v156, 16, v241
	v_and_b32_e32 v157, 0xffff0000, v241
	v_lshlrev_b32_e32 v166, 16, v242
	v_and_b32_e32 v167, 0xffff0000, v242
	v_lshlrev_b32_e32 v158, 16, v243
	v_and_b32_e32 v159, 0xffff0000, v243
	v_pk_add_f32 v[30:31], v[30:31], v[156:157]
	v_pk_add_f32 v[28:29], v[28:29], v[164:165]
	v_pk_add_f32 v[26:27], v[26:27], v[158:159]
	v_pk_add_f32 v[24:25], v[24:25], v[166:167]
	global_store_dwordx4 v[162:163], v[28:31], off nt
	global_store_dwordx4 v[162:163], v[24:27], off offset:16 nt
	s_waitcnt vmcnt(16)
	v_lshlrev_b32_e32 v164, 16, v244
	v_and_b32_e32 v165, 0xffff0000, v244
	v_lshlrev_b32_e32 v156, 16, v245
	v_and_b32_e32 v157, 0xffff0000, v245
	v_lshlrev_b32_e32 v166, 16, v246
	v_and_b32_e32 v167, 0xffff0000, v246
	v_lshlrev_b32_e32 v158, 16, v247
	v_and_b32_e32 v159, 0xffff0000, v247
	v_pk_add_f32 v[22:23], v[22:23], v[156:157]
	v_pk_add_f32 v[20:21], v[20:21], v[164:165]
	v_pk_add_f32 v[18:19], v[18:19], v[158:159]
	v_pk_add_f32 v[16:17], v[16:17], v[166:167]
	global_store_dwordx4 v[162:163], v[20:23], off offset:512 nt
	global_store_dwordx4 v[162:163], v[16:19], off offset:528 nt
	v_or_b32_e32 v144, 0xb0, v148
	v_ashrrev_i32_e32 v145, 31, v144
	v_lshlrev_b64 v[144:145], 11, v[144:145]
	v_lshl_add_u64 v[144:145], v[144:145], 0, v[146:147]
	v_lshl_add_u64 v[162:163], v[144:145], 2, s[58:59]
	s_waitcnt vmcnt(13)
	v_lshlrev_b32_e32 v164, 16, v248
	v_and_b32_e32 v165, 0xffff0000, v248
	v_lshlrev_b32_e32 v156, 16, v249
	v_and_b32_e32 v157, 0xffff0000, v249
	v_lshlrev_b32_e32 v166, 16, v250
	v_and_b32_e32 v167, 0xffff0000, v250
	v_lshlrev_b32_e32 v158, 16, v251
	v_and_b32_e32 v159, 0xffff0000, v251
	v_pk_add_f32 v[14:15], v[14:15], v[156:157]
	v_pk_add_f32 v[12:13], v[12:13], v[164:165]
	v_pk_add_f32 v[10:11], v[10:11], v[158:159]
	v_pk_add_f32 v[8:9], v[8:9], v[166:167]
	global_store_dwordx4 v[162:163], v[12:15], off nt
	global_store_dwordx4 v[162:163], v[8:11], off offset:16 nt
	s_waitcnt vmcnt(14)
	v_lshlrev_b32_e32 v164, 16, v252
	v_and_b32_e32 v165, 0xffff0000, v252
	v_lshlrev_b32_e32 v156, 16, v253
	v_and_b32_e32 v157, 0xffff0000, v253
	v_lshlrev_b32_e32 v166, 16, v254
	v_and_b32_e32 v167, 0xffff0000, v254
	v_lshlrev_b32_e32 v158, 16, v255
	v_and_b32_e32 v159, 0xffff0000, v255
	v_pk_add_f32 v[6:7], v[6:7], v[156:157]
	v_pk_add_f32 v[4:5], v[4:5], v[164:165]
	v_pk_add_f32 v[2:3], v[2:3], v[158:159]
	v_pk_add_f32 v[0:1], v[0:1], v[166:167]
	global_store_dwordx4 v[162:163], v[4:7], off offset:512 nt
	global_store_dwordx4 v[162:163], v[0:3], off offset:528 nt
	s_cbranch_vccnz .LBB0_779
	s_andn2_b64 vcc, exec, s[4:5]
	s_cbranch_vccnz .LBB0_778
	s_barrier
	s_branch .LBB0_778
